# RG-LRU apply carry prologue: the context item's aggregate load flies with the 31 latent loads (one memory round trip less per workgroup)
# baseline (speedup 1.0000x reference)
.LBB0_311:
	s_or_b64 exec, exec, s[8:9]
	s_and_b64 s[0:1], exec, s[0:1]
	s_or_b64 s[6:7], s[0:1], s[6:7]
	s_waitcnt vmcnt(0)
	ds_write_b32 v152, v34
	v_cndmask_b32_e64 v251, 0, v249, s[98:99]
	ds_write_b32 v250, v251
	v_add_u32_e32 v118, 4, v118
	v_add_u32_e32 v79, 64, v79
	v_add_u32_e32 v151, 32, v151
	v_add_u32_e32 v152, 0x800, v152
	s_andn2_b64 exec, exec, s[6:7]
	s_cbranch_execz .LBB0_504

.LBB0_440:
	s_andn2_saveexec_b64 s[8:9], s[8:9]
	s_cbranch_execz .LBB0_311
	s_waitcnt vmcnt(1)
	v_lshl_or_b32 v42, v153, 4, s18
	v_ashrrev_i32_e32 v43, 31, v42
	v_lshlrev_b64 v[42:43], 10, v[42:43]
	v_lshl_add_u64 v[42:43], v[40:41], 0, v[42:43]
	global_load_dwordx2 v[248:249], v[42:43], off offset:512 sc1
	v_and_b32_e32 v34, 1, v153
	v_cmp_eq_u32_e64 s[4:5], 0, v34
	s_and_b64 s[98:99], vcc, s[4:5]
	v_mov_b32_e32 v250, v152
	s_or_b64 exec, exec, s[8:9]
	s_and_b64 s[0:1], exec, s[0:1]
	s_or_b64 s[6:7], s[0:1], s[6:7]
	v_add_u32_e32 v118, 4, v118
	v_add_u32_e32 v79, 64, v79
	v_add_u32_e32 v151, 32, v151
	v_add_u32_e32 v152, 0x800, v152
	s_andn2_b64 exec, exec, s[6:7]
	s_cbranch_execz .LBB0_504
	s_branch .LBB0_312
